# cmp1 (phase 4 long compress GEMM) k-loop rescheduled like the other GEMM loops: loads/LDS writes interleaved with MFMAs, double-buffered fragment reads
# speedup vs baseline: 1.0018x; 1.0018x over previous
; #define G_STORE(ST, S, unused) do { char* d_ = smem + (ST) * STAGE; \
;     *(uint4*)(d_ + alo[0]) = S##a0; *(uint4*)(d_ + alo[1]) = S##a1; *(uint4*)(d_ + alo[2]) = S##a2; *(uint4*)(d_ + alo[3]) = S##a3; \
;     *(uint4*)(d_ + blo[0]) = S##b0; *(uint4*)(d_ + blo[1]) = S##b1; \
;     if (NBCH == 4) { *(uint4*)(d_ + blo[NBCH - 2]) = S##b2; *(uint4*)(d_ + blo[NBCH - 1]) = S##b3; } } while (0)
; template <int NJ, class RowA>
; DI void gemm_main(f32x16 (&acc)[2][NJ], const bf16_t* __restrict__ A, RowA rowA, size_t kstrideA, int m0, int Mmax,
;                   const bf16_t* __restrict__ Bt, size_t ldb, int n0, int nk, char* smem) {
;     ...
;   __syncthreads();
;   G_LOAD(x0, 0, 0);
;   G_LOAD(x1, 0, 1);
;   G_STORE(0, x0, 0);
;   __syncthreads();
; #pragma unroll 1
;   for (int kt = 0; kt < nk; kt += 2) {
;     G_LOAD(x0, 0, (kt + 2 < nk ? kt + 2 : nk - 1));
;     G_COMPUTE(0);
;     G_STORE(1, x1, 0);
;     __syncthreads();
;     G_LOAD(x1, 0, (kt + 3 < nk ? kt + 3 : nk - 1));
;     G_COMPUTE(1);
;     G_STORE(0, x0, 0);
;     __syncthreads();
.LBB0_1313:
	ds_read_b128 v[190:193], v0
	ds_read_b128 v[194:197], v139 offset:18432
	ds_read_b128 v[198:201], v139 offset:23040
	ds_read_b128 v[202:205], v0 offset:4608
	s_add_i32 s9, s1, 2
	s_cmp_lt_u32 s1, 30
	s_cselect_b64 s[10:11], -1, 0
	s_and_b64 vcc, s[10:11], exec
	s_cselect_b32 s14, s9, 31
	v_mad_u64_u32 v[98:99], s[10:11], s14, v238, v[122:123]
	v_mad_u64_u32 v[102:103], s[10:11], s14, v238, v[124:125]
	v_mad_u64_u32 v[106:107], s[10:11], s14, v238, v[126:127]
	v_mad_u64_u32 v[110:111], s[10:11], s14, v238, v[128:129]
	s_lshl_b64 s[10:11], s[14:15], 7
	s_nop 0
	v_lshl_add_u64 v[114:115], v[130:131], 0, s[10:11]
	v_lshl_add_u64 v[118:119], v[132:133], 0, s[10:11]
	v_lshl_add_u64 v[158:159], v[134:135], 0, s[10:11]
	v_lshl_add_u64 v[160:161], v[136:137], 0, s[10:11]
	s_setprio 1
	ds_read_b128 v[172:175], v0 offset:32
	ds_read_b128 v[176:179], v139 offset:18464
	ds_read_b128 v[180:183], v139 offset:23072
	ds_read_b128 v[216:219], v0 offset:4640
	s_waitcnt lgkmcnt(4)
	v_mfma_f32_32x32x16_bf16 v[50:65], v[190:193], v[194:197], v[50:65]
	global_load_dwordx4 v[98:101], v[98:99], off
	v_mfma_f32_32x32x16_bf16 v[34:49], v[190:193], v[198:201], v[34:49]
	global_load_dwordx4 v[102:105], v[102:103], off
	v_mfma_f32_32x32x16_bf16 v[18:33], v[202:205], v[194:197], v[18:33]
	global_load_dwordx4 v[106:109], v[106:107], off
	v_mfma_f32_32x32x16_bf16 v[2:17], v[202:205], v[198:201], v[2:17]
	global_load_dwordx4 v[110:113], v[110:111], off
	ds_read_b128 v[190:193], v0 offset:64
	ds_read_b128 v[194:197], v139 offset:18496
	ds_read_b128 v[198:201], v139 offset:23104
	ds_read_b128 v[202:205], v0 offset:4672
	s_waitcnt lgkmcnt(4)
	v_mfma_f32_32x32x16_bf16 v[50:65], v[172:175], v[176:179], v[50:65]
	global_load_dwordx4 v[114:117], v[114:115], off
	s_waitcnt vmcnt(5)
	ds_write_b128 v138, v[74:77] offset:36864
	v_mfma_f32_32x32x16_bf16 v[34:49], v[172:175], v[180:183], v[34:49]
	global_load_dwordx4 v[118:121], v[118:119], off
	ds_write_b128 v140, v[78:81] offset:36864
	v_mfma_f32_32x32x16_bf16 v[18:33], v[216:219], v[176:179], v[18:33]
	global_load_dwordx4 v[146:149], v[160:161], off
	ds_write_b128 v142, v[82:85] offset:36864
	v_mfma_f32_32x32x16_bf16 v[2:17], v[216:219], v[180:183], v[2:17]
	global_load_dwordx4 v[150:153], v[158:159], off
	ds_write_b128 v144, v[86:89] offset:36864
	ds_read_b128 v[172:175], v0 offset:96
	ds_read_b128 v[176:179], v139 offset:18528
	ds_read_b128 v[180:183], v139 offset:23136
	ds_read_b128 v[216:219], v0 offset:4704
	s_waitcnt lgkmcnt(8)
	v_mfma_f32_32x32x16_bf16 v[50:65], v[190:193], v[194:197], v[50:65]
	ds_write_b128 v138, v[90:93] offset:55296
	v_mfma_f32_32x32x16_bf16 v[34:49], v[190:193], v[198:201], v[34:49]
	ds_write_b128 v140, v[94:97] offset:55296
	v_mfma_f32_32x32x16_bf16 v[18:33], v[202:205], v[194:197], v[18:33]
	ds_write_b128 v142, v[66:69] offset:55296
	v_mfma_f32_32x32x16_bf16 v[2:17], v[202:205], v[198:201], v[2:17]
	ds_write_b128 v144, v[70:73] offset:55296
	s_waitcnt lgkmcnt(4)
	v_mfma_f32_32x32x16_bf16 v[50:65], v[172:175], v[176:179], v[50:65]
	v_mfma_f32_32x32x16_bf16 v[34:49], v[172:175], v[180:183], v[34:49]
	v_mfma_f32_32x32x16_bf16 v[18:33], v[216:219], v[176:179], v[18:33]
	v_mfma_f32_32x32x16_bf16 v[2:17], v[216:219], v[180:183], v[2:17]
	s_setprio 0
	s_min_u32 s1, s1, 28
	s_add_i32 s1, s1, 3
	s_mul_i32 s14, s1, 0xd00
	v_lshl_add_u64 v[66:67], v[122:123], 0, s[14:15]
	v_lshl_add_u64 v[68:69], v[124:125], 0, s[14:15]
	v_lshl_add_u64 v[70:71], v[126:127], 0, s[14:15]
	v_lshl_add_u64 v[72:73], v[128:129], 0, s[14:15]
	s_lshl_b32 s14, s1, 7
	v_lshl_add_u64 v[90:91], v[130:131], 0, s[14:15]
	v_lshl_add_u64 v[94:95], v[132:133], 0, s[14:15]
	s_waitcnt lgkmcnt(0)
	s_barrier
; #define TIDX (tid_launder())
; DI int crow(int reg, int hh) { return (reg & 3) + 8 * (reg >> 2) + 4 * hh; }
; #define G_STORE(ST, S, unused) do { char* d_ = smem + (ST) * STAGE; \
;     *(uint4*)(d_ + alo[0]) = S##a0; *(uint4*)(d_ + alo[1]) = S##a1; *(uint4*)(d_ + alo[2]) = S##a2; *(uint4*)(d_ + alo[3]) = S##a3; \
;     *(uint4*)(d_ + blo[0]) = S##b0; *(uint4*)(d_ + blo[1]) = S##b1; \
;     if (NBCH == 4) { *(uint4*)(d_ + blo[NBCH - 2]) = S##b2; *(uint4*)(d_ + blo[NBCH - 1]) = S##b3; } } while (0)
; template <int NJ, class RowA>
; DI void gemm_main(f32x16 (&acc)[2][NJ], const bf16_t* __restrict__ A, RowA rowA, size_t kstrideA, int m0, int Mmax,
;                   const bf16_t* __restrict__ Bt, size_t ldb, int n0, int nk, char* smem) {
;     ...
;     G_LOAD(x0, 0, (kt + 2 < nk ? kt + 2 : nk - 1));
;     G_COMPUTE(0);
;     G_STORE(1, x1, 0);
;     __syncthreads();
;     G_LOAD(x1, 0, (kt + 3 < nk ? kt + 3 : nk - 1));
;     G_COMPUTE(1);
;     G_STORE(0, x0, 0);
;     __syncthreads();
;   }
;     ...
; }
; template <int NJ>
; DI void acc_to_ct(const f32x16 (&acc)[2][NJ], float* Ct) {
;   const int lane = TIDX & 63, wid = TIDX >> 6, wm = wid >> 1, wn = wid & 1;
;   const int r = lane & 31, hh = lane >> 5;
; #pragma unroll
;   for (int i = 0; i < 2; ++i)
; #pragma unroll
;     for (int j = 0; j < NJ; ++j)
; #pragma unroll
;       for (int e = 0; e < 16; ++e) Ct[(wm * 64 + i * 32 + crow(e, hh)) * 132 + wn * 32 * NJ + j * 32 + r] = acc[i][j][e];
;   __syncthreads();
	ds_read_b128 v[190:193], v0 offset:36864
	ds_read_b128 v[194:197], v139 offset:55296
	ds_read_b128 v[198:201], v139 offset:59904
	ds_read_b128 v[202:205], v0 offset:41472
	v_lshl_add_u64 v[154:155], v[134:135], 0, s[14:15]
	v_lshl_add_u64 v[156:157], v[136:137], 0, s[14:15]
	s_setprio 1
	ds_read_b128 v[172:175], v0 offset:36896
	ds_read_b128 v[176:179], v139 offset:55328
	ds_read_b128 v[180:183], v139 offset:59936
	ds_read_b128 v[216:219], v0 offset:41504
	s_waitcnt lgkmcnt(4)
	v_mfma_f32_32x32x16_bf16 v[50:65], v[190:193], v[194:197], v[50:65]
	global_load_dwordx4 v[74:77], v[66:67], off
	v_mfma_f32_32x32x16_bf16 v[34:49], v[190:193], v[198:201], v[34:49]
	global_load_dwordx4 v[78:81], v[68:69], off
	v_mfma_f32_32x32x16_bf16 v[18:33], v[202:205], v[194:197], v[18:33]
	global_load_dwordx4 v[82:85], v[70:71], off
	v_mfma_f32_32x32x16_bf16 v[2:17], v[202:205], v[198:201], v[2:17]
	global_load_dwordx4 v[86:89], v[72:73], off
	ds_read_b128 v[190:193], v0 offset:36928
	ds_read_b128 v[194:197], v139 offset:55360
	ds_read_b128 v[198:201], v139 offset:59968
	ds_read_b128 v[202:205], v0 offset:41536
	s_waitcnt lgkmcnt(4)
	v_mfma_f32_32x32x16_bf16 v[50:65], v[172:175], v[176:179], v[50:65]
	global_load_dwordx4 v[90:93], v[90:91], off
	s_waitcnt vmcnt(5)
	ds_write_b128 v138, v[98:101]
	v_mfma_f32_32x32x16_bf16 v[34:49], v[172:175], v[180:183], v[34:49]
	global_load_dwordx4 v[94:97], v[94:95], off
	ds_write_b128 v140, v[102:105]
	v_mfma_f32_32x32x16_bf16 v[18:33], v[216:219], v[176:179], v[18:33]
	global_load_dwordx4 v[66:69], v[154:155], off
	ds_write_b128 v142, v[106:109]
	v_mfma_f32_32x32x16_bf16 v[2:17], v[216:219], v[180:183], v[2:17]
	global_load_dwordx4 v[70:73], v[156:157], off
	ds_write_b128 v144, v[110:113]
	ds_read_b128 v[172:175], v0 offset:36960
	ds_read_b128 v[176:179], v139 offset:55392
	ds_read_b128 v[180:183], v139 offset:60000
	ds_read_b128 v[216:219], v0 offset:41568
	s_waitcnt lgkmcnt(8)
	v_mfma_f32_32x32x16_bf16 v[50:65], v[190:193], v[194:197], v[50:65]
	ds_write_b128 v138, v[114:117] offset:18432
	v_mfma_f32_32x32x16_bf16 v[34:49], v[190:193], v[198:201], v[34:49]
	ds_write_b128 v140, v[118:121] offset:18432
	v_mfma_f32_32x32x16_bf16 v[18:33], v[202:205], v[194:197], v[18:33]
	ds_write_b128 v142, v[150:153] offset:18432
	v_mfma_f32_32x32x16_bf16 v[2:17], v[202:205], v[198:201], v[2:17]
	ds_write_b128 v144, v[146:149] offset:18432
	s_waitcnt lgkmcnt(4)
	v_mfma_f32_32x32x16_bf16 v[50:65], v[172:175], v[176:179], v[50:65]
	v_mfma_f32_32x32x16_bf16 v[34:49], v[172:175], v[180:183], v[34:49]
	v_mfma_f32_32x32x16_bf16 v[18:33], v[216:219], v[176:179], v[18:33]
	v_mfma_f32_32x32x16_bf16 v[2:17], v[216:219], v[180:183], v[2:17]
	s_setprio 0
	s_mov_b32 s1, s9
	s_waitcnt lgkmcnt(0)
	s_barrier
	s_cbranch_vccnz .LBB0_1313
	v_mov_b32_e32 v0, v230
	s_waitcnt vmcnt(1)
	v_mov_b32_e32 v66, v230
	v_and_b32_e32 v67, 31, v0
	v_lshrrev_b32_e32 v0, 3, v0
	v_and_b32_e32 v0, 4, v0
	v_lshrrev_b32_e32 v68, 1, v66
	v_and_or_b32 v0, v68, s47, v0
	v_and_or_b32 v66, v66, 64, v67
	v_mul_lo_u32 v0, v0, s79
	v_lshl_add_u32 v0, v66, 2, v0
	ds_write2_b32 v0, v50, v34 offset1:32
	ds_write2_b32 v0, v51, v35 offset0:132 offset1:164
	v_add_u32_e32 v34, 0x400, v0
	ds_write2_b32 v34, v52, v36 offset0:8 offset1:40
	ds_write2_b32 v34, v53, v37 offset0:140 offset1:172
	v_add_u32_e32 v34, 0x1000, v0
	ds_write2_b32 v34, v54, v38 offset0:32 offset1:64
	ds_write2_b32 v34, v55, v39 offset0:164 offset1:196
	v_add_u32_e32 v34, 0x1400, v0
	ds_write2_b32 v34, v56, v40 offset0:40 offset1:72
	ds_write2_b32 v34, v57, v41 offset0:172 offset1:204
	v_add_u32_e32 v34, 0x2000, v0
	ds_write2_b32 v34, v58, v42 offset0:64 offset1:96
	ds_write2_b32 v34, v59, v43 offset0:196 offset1:228
	v_add_u32_e32 v34, 0x2400, v0
	ds_write2_b32 v34, v60, v44 offset0:72 offset1:104
	ds_write2_b32 v34, v61, v45 offset0:204 offset1:236
	v_add_u32_e32 v34, 0x3000, v0
	ds_write2_b32 v34, v62, v46 offset0:96 offset1:128
	v_add_u32_e32 v34, 0x3200, v0
	ds_write2_b32 v34, v63, v47 offset0:100 offset1:132
	v_add_u32_e32 v34, 0x3400, v0
	ds_write2_b32 v34, v64, v48 offset0:104 offset1:136
	v_add_u32_e32 v34, 0x3600, v0
	ds_write2_b32 v34, v65, v49 offset0:108 offset1:140
	v_add_u32_e32 v34, 0x4000, v0
	ds_write2_b32 v34, v18, v2 offset0:128 offset1:160
	v_add_u32_e32 v2, 0x4400, v0
	ds_write2_b32 v2, v19, v3 offset0:4 offset1:36
	ds_write2_b32 v2, v20, v4 offset0:136 offset1:168
	v_add_u32_e32 v2, 0x4800, v0
	ds_write2_b32 v2, v21, v5 offset0:12 offset1:44
	v_add_u32_e32 v2, 0x5000, v0
	ds_write2_b32 v2, v22, v6 offset0:160 offset1:192
	v_add_u32_e32 v2, 0x5400, v0
	ds_write2_b32 v2, v23, v7 offset0:36 offset1:68
	ds_write2_b32 v2, v24, v8 offset0:168 offset1:200
	v_add_u32_e32 v2, 0x5800, v0
	ds_write2_b32 v2, v25, v9 offset0:44 offset1:76
	v_add_u32_e32 v2, 0x6000, v0
	ds_write2_b32 v2, v26, v10 offset0:192 offset1:224
	v_add_u32_e32 v2, 0x6400, v0
	ds_write2_b32 v2, v27, v11 offset0:68 offset1:100
	ds_write2_b32 v2, v28, v12 offset0:200 offset1:232
	v_add_u32_e32 v2, 0x6800, v0
	ds_write2_b32 v2, v29, v13 offset0:76 offset1:108
	v_add_u32_e32 v2, 0x7200, v0
	ds_write2_b32 v2, v30, v14 offset0:96 offset1:128
	v_add_u32_e32 v2, 0x7400, v0
	ds_write2_b32 v2, v31, v15 offset0:100 offset1:132
	v_add_u32_e32 v2, 0x7600, v0
	v_add_u32_e32 v0, 0x7800, v0
	ds_write2_b32 v0, v33, v17 offset0:108 offset1:140
	v_mov_b32_e32 v0, v230
	v_readlane_b32 s10, v251, 27
	ds_write2_b32 v2, v32, v16 offset0:104 offset1:136
	s_waitcnt lgkmcnt(0)
	s_barrier
	s_lshl_b32 s0, s0, 8
	v_readlane_b32 s11, v251, 28
	v_lshlrev_b32_e32 v2, 2, v0
	s_ashr_i32 s1, s0, 31
	s_andn2_b64 vcc, exec, s[10:11]
	v_and_b32_e32 v8, 60, v2
	s_cbranch_vccz .LBB0_1248
	v_mov_b32_e32 v4, 0
	v_readlane_b32 s36, v252, 57
	v_mov_b32_e32 v5, v4
	v_mov_b32_e32 v2, v4
	v_mov_b32_e32 v3, v4
	v_readlane_b32 s37, v252, 58
	v_readlane_b32 s38, v252, 59
	v_readlane_b32 s39, v252, 60
	v_readlane_b32 s40, v252, 61
	v_readlane_b32 s41, v252, 62
	s_branch .LBB0_1249
